# v7 + GLU epilogue: second-half y/z loads software-pipelined into first half (renamed regs, counted waits), final store drain before attention removed
# speedup vs baseline: 1.0100x; 1.0100x over previous
; __device__ __forceinline__ unsigned pk2(float lo, float hi) { const f32x2c_t v = {lo, hi}; return __builtin_bit_cast(unsigned, __builtin_convertvector(v, bf16x2c_t)); }
; __device__ __forceinline__ float bflo(unsigned w) { return __uint_as_float(w << 16); }
; __device__ __forceinline__ float bfhi(unsigned w) { return __uint_as_float(w & 0xffff0000u); }
; __device__ __forceinline__ float sigmoidf_(float v) { return __builtin_amdgcn_rcpf(1.f + __expf(-v)); }
;     __device__ __forceinline__ void operator()(const f32x4 (&acc)[2][2][4][2], const Unit& u, int wr, int wc, int fr, int fq) const {
;     ...
;             for (int n = 0; n < 2; ++n) bias[bj][n] = *(const f32x4*)(bglu + 256 * u.pn + 64 * wc + 32 * bj + 8 * fq + 4 * n);
; #pragma unroll
;         for (int ai = 0; ai < 2; ++ai) {
;             u32x4 y4[4][2], z4[4][2];
; #pragma unroll
;             for (int m = 0; m < 4; ++m) {
;                 const int row = 256 * u.pm + 128 * ai + 64 * wr + 16 * m + fr;
; #pragma unroll
;                 for (int bj = 0; bj < 2; ++bj) {
;                     const unsigned off = (unsigned)row * 512u + (unsigned)(256 * u.pn + 64 * wc + 32 * bj + 8 * fq);
;                     y4[m][bj] = *(const u32x4*)(YG + off); z4[m][bj] = *(const u32x4*)(SZS + off);
;                 }
;             }
; #pragma unroll
;             for (int m = 0; m < 4; ++m) {
;                 const int row = 256 * u.pm + 128 * ai + 64 * wr + 16 * m + fr;
; #pragma unroll
;                 for (int bj = 0; bj < 2; ++bj) {
;                     const int col = 256 * u.pn + 64 * wc + 32 * bj + 8 * fq;
;                     unsigned w[4];
; #pragma unroll
;                     for (int n = 0; n < 2; ++n) {
;                         const f32x4 a = acc[ai][bj][m][n] + bias[bj][n];
;                         const unsigned ya = y4[m][bj][2 * n], yb = y4[m][bj][2 * n + 1], za = z4[m][bj][2 * n], zb = z4[m][bj][2 * n + 1];
;                         const float o0 = bflo(ya) * sigmoidf_(a[0]) * bflo(za), o1 = bfhi(ya) * sigmoidf_(a[1]) * bfhi(za);
;                         const float o2 = bflo(yb) * sigmoidf_(a[2]) * bflo(zb), o3 = bfhi(yb) * sigmoidf_(a[3]) * bfhi(zb);
;                         w[2 * n] = pk2(o0, o1); w[2 * n + 1] = pk2(o2, o3);
;                     }
;                     *(u32x4*)(MIXED + (size_t)row * 1024 + 512 + col) = (u32x4){w[0], w[1], w[2], w[3]};
;                 }
.LBB0_329:
	s_lshl_b32 s0, s34, 10
	s_add_u32 s0, s70, s0
	s_addc_u32 s1, s71, 0
	s_lshl_b32 s3, s37, 8
	s_add_u32 s0, s0, s3
	v_lshl_or_b32 v66, s34, 8, v75
	s_addc_u32 s1, s1, 0
	v_lshlrev_b32_e32 v160, 2, v75
	v_lshl_add_u32 v204, s16, 8, v74
	v_lshl_or_b32 v199, s37, 6, v66
	global_load_dwordx4 v[78:81], v160, s[0:1]
	v_lshl_or_b32 v202, v204, 9, v199
	v_mov_b32_e32 v203, 0
	v_lshlrev_b64 v[66:67], 1, v[202:203]
	v_lshl_add_u64 v[68:69], s[4:5], 0, v[66:67]
	v_lshl_add_u64 v[66:67], s[14:15], 0, v[66:67]
	global_load_dwordx4 v[208:211], v[68:69], off
	global_load_dwordx4 v[214:217], v[66:67], off
	global_load_dwordx4 v[70:73], v160, s[0:1] offset:16
	v_mov_b32_e32 v67, v203
	v_mov_b32_e32 v69, v203
	v_mov_b32_e32 v75, v203
	v_mov_b32_e32 v77, v203
	v_or_b32_e32 v66, 32, v202
	v_or_b32_e32 v68, 0x2000, v202
	v_or_b32_e32 v74, 0x2020, v202
	v_or_b32_e32 v76, 0x4000, v202
	v_lshlrev_b64 v[144:145], 1, v[66:67]
	v_lshlrev_b64 v[154:155], 1, v[68:69]
	v_lshlrev_b64 v[156:157], 1, v[74:75]
	v_lshlrev_b64 v[158:159], 1, v[76:77]
	global_load_dwordx4 v[66:69], v160, s[0:1] offset:144
	global_load_dwordx4 v[74:77], v160, s[0:1] offset:128
	v_mov_b32_e32 v139, v203
	v_mov_b32_e32 v141, v203
	v_or_b32_e32 v138, 0x4020, v202
	v_or_b32_e32 v140, 0x6000, v202
	v_mov_b32_e32 v143, v203
	v_or_b32_e32 v142, 0x6020, v202
	v_lshlrev_b64 v[138:139], 1, v[138:139]
	v_lshlrev_b64 v[140:141], 1, v[140:141]
	v_lshlrev_b64 v[142:143], 1, v[142:143]
	v_lshl_add_u64 v[160:161], s[4:5], 0, v[144:145]
	v_lshl_add_u64 v[144:145], s[14:15], 0, v[144:145]
	v_lshl_add_u64 v[162:163], s[4:5], 0, v[154:155]
	v_lshl_add_u64 v[154:155], s[14:15], 0, v[154:155]
	v_lshl_add_u64 v[164:165], s[4:5], 0, v[156:157]
	v_lshl_add_u64 v[156:157], s[14:15], 0, v[156:157]
	v_lshl_add_u64 v[166:167], s[4:5], 0, v[158:159]
	v_lshl_add_u64 v[158:159], s[14:15], 0, v[158:159]
	v_lshl_add_u64 v[168:169], s[4:5], 0, v[138:139]
	v_lshl_add_u64 v[138:139], s[14:15], 0, v[138:139]
	v_lshl_add_u64 v[228:229], s[4:5], 0, v[140:141]
	v_lshl_add_u64 v[140:141], s[14:15], 0, v[140:141]
	v_lshl_add_u64 v[230:231], s[4:5], 0, v[142:143]
	v_lshl_add_u64 v[232:233], s[14:15], 0, v[142:143]
	global_load_dwordx4 v[218:221], v[160:161], off
	global_load_dwordx4 v[222:225], v[144:145], off
	global_load_dwordx4 v[190:193], v[162:163], off
	global_load_dwordx4 v[186:189], v[154:155], off
	global_load_dwordx4 v[182:185], v[164:165], off
	global_load_dwordx4 v[178:181], v[156:157], off
	global_load_dwordx4 v[174:177], v[166:167], off
	global_load_dwordx4 v[170:173], v[158:159], off
	s_nop 0
	global_load_dwordx4 v[166:169], v[168:169], off
	s_nop 0
	global_load_dwordx4 v[162:165], v[138:139], off
	global_load_dwordx4 v[158:161], v[228:229], off
	global_load_dwordx4 v[154:157], v[140:141], off
	global_load_dwordx4 v[142:145], v[230:231], off
	s_nop 0
	global_load_dwordx4 v[138:141], v[232:233], off
	v_ashrrev_i32_e32 v205, 31, v204
	v_lshlrev_b64 v[226:227], 11, v[204:205]
	s_mov_b64 s[0:1], 0x40000
	s_waitcnt vmcnt(0)
	v_pk_add_f32 v[152:153], v[152:153], v[80:81]
	v_pk_add_f32 v[150:151], v[150:151], v[78:79]
	v_mul_f32_e32 v152, 0xbfb8aa3b, v152
	v_mul_f32_e32 v150, 0xbfb8aa3b, v150
	v_mul_f32_e32 v151, 0xbfb8aa3b, v151
	v_mul_f32_e32 v153, 0xbfb8aa3b, v153
	v_exp_f32_e32 v150, v150
	v_exp_f32_e32 v151, v151
	v_exp_f32_e32 v152, v152
	v_exp_f32_e32 v153, v153
	v_pk_add_f32 v[146:147], v[146:147], v[70:71]
	v_pk_add_f32 v[148:149], v[148:149], v[72:73]
	v_mul_f32_e32 v146, 0xbfb8aa3b, v146
	v_mul_f32_e32 v147, 0xbfb8aa3b, v147
	v_exp_f32_e32 v146, v146
	v_exp_f32_e32 v147, v147
	v_add_f32_e32 v150, 1.0, v150
	v_add_f32_e32 v151, 1.0, v151
	v_add_f32_e32 v152, 1.0, v152
	v_add_f32_e32 v153, 1.0, v153
	v_mul_f32_e32 v148, 0xbfb8aa3b, v148
	v_mul_f32_e32 v149, 0xbfb8aa3b, v149
	v_rcp_f32_e32 v150, v150
	v_rcp_f32_e32 v151, v151
	v_rcp_f32_e32 v152, v152
	v_rcp_f32_e32 v153, v153
	v_exp_f32_e32 v148, v148
	v_exp_f32_e32 v149, v149
	v_add_f32_e32 v146, 1.0, v146
	v_add_f32_e32 v147, 1.0, v147
	v_lshlrev_b32_e32 v228, 16, v208
	v_and_b32_e32 v229, 0xffff0000, v208
	v_lshlrev_b32_e32 v208, 16, v209
	v_and_b32_e32 v209, 0xffff0000, v209
	v_rcp_f32_e32 v146, v146
	v_rcp_f32_e32 v147, v147
	v_pk_add_f32 v[134:135], v[134:135], v[74:75]
	v_lshlrev_b32_e32 v230, 16, v214
	v_and_b32_e32 v231, 0xffff0000, v214
	v_pk_mul_f32 v[150:151], v[150:151], v[228:229]
	v_pk_mul_f32 v[152:153], v[152:153], v[208:209]
	v_lshlrev_b32_e32 v208, 16, v215
	v_and_b32_e32 v209, 0xffff0000, v215
	v_add_f32_e32 v148, 1.0, v148
	v_add_f32_e32 v149, 1.0, v149
	v_mul_f32_e32 v134, 0xbfb8aa3b, v134
	v_mul_f32_e32 v135, 0xbfb8aa3b, v135
	v_pk_mul_f32 v[150:151], v[150:151], v[230:231]
	v_pk_mul_f32 v[152:153], v[152:153], v[208:209]
	v_rcp_f32_e32 v148, v148
	v_rcp_f32_e32 v149, v149
	v_exp_f32_e32 v134, v134
	v_exp_f32_e32 v135, v135
	v_pk_add_f32 v[136:137], v[136:137], v[76:77]
	v_cvt_pk_bf16_f32 v150, v150, v151
	v_cvt_pk_bf16_f32 v151, v152, v153
	v_lshlrev_b32_e32 v152, 16, v210
	v_and_b32_e32 v153, 0xffff0000, v210
	v_mul_f32_e32 v136, 0xbfb8aa3b, v136
	v_mul_f32_e32 v137, 0xbfb8aa3b, v137
	v_pk_mul_f32 v[146:147], v[146:147], v[152:153]
	v_lshlrev_b32_e32 v152, 16, v216
	v_and_b32_e32 v153, 0xffff0000, v216
	v_exp_f32_e32 v136, v136
	v_exp_f32_e32 v137, v137
	v_pk_mul_f32 v[146:147], v[146:147], v[152:153]
	v_lshlrev_b32_e32 v152, 16, v211
	v_and_b32_e32 v153, 0xffff0000, v211
	v_pk_add_f32 v[130:131], v[130:131], v[66:67]
	v_pk_mul_f32 v[148:149], v[148:149], v[152:153]
	v_lshlrev_b32_e32 v152, 16, v217
	v_and_b32_e32 v153, 0xffff0000, v217
	v_add_f32_e32 v134, 1.0, v134
	v_add_f32_e32 v135, 1.0, v135
	v_mul_f32_e32 v130, 0xbfb8aa3b, v130
; __device__ __forceinline__ unsigned pk2(float lo, float hi) { const f32x2c_t v = {lo, hi}; return __builtin_bit_cast(unsigned, __builtin_convertvector(v, bf16x2c_t)); }
; __device__ __forceinline__ float bflo(unsigned w) { return __uint_as_float(w << 16); }
; __device__ __forceinline__ float bfhi(unsigned w) { return __uint_as_float(w & 0xffff0000u); }
; __device__ __forceinline__ float sigmoidf_(float v) { return __builtin_amdgcn_rcpf(1.f + __expf(-v)); }
;     __device__ __forceinline__ void operator()(const f32x4 (&acc)[2][2][4][2], const Unit& u, int wr, int wc, int fr, int fq) const {
;     ...
;         for (int ai = 0; ai < 2; ++ai) {
;             u32x4 y4[4][2], z4[4][2];
; #pragma unroll
;             for (int m = 0; m < 4; ++m) {
;                 const int row = 256 * u.pm + 128 * ai + 64 * wr + 16 * m + fr;
; #pragma unroll
;                 for (int bj = 0; bj < 2; ++bj) {
;                     const unsigned off = (unsigned)row * 512u + (unsigned)(256 * u.pn + 64 * wc + 32 * bj + 8 * fq);
;                     y4[m][bj] = *(const u32x4*)(YG + off); z4[m][bj] = *(const u32x4*)(SZS + off);
;                 }
;             }
; #pragma unroll
;             for (int m = 0; m < 4; ++m) {
;                 const int row = 256 * u.pm + 128 * ai + 64 * wr + 16 * m + fr;
; #pragma unroll
;                 for (int bj = 0; bj < 2; ++bj) {
;                     const int col = 256 * u.pn + 64 * wc + 32 * bj + 8 * fq;
;                     unsigned w[4];
; #pragma unroll
;                     for (int n = 0; n < 2; ++n) {
;                         const f32x4 a = acc[ai][bj][m][n] + bias[bj][n];
;                         const unsigned ya = y4[m][bj][2 * n], yb = y4[m][bj][2 * n + 1], za = z4[m][bj][2 * n], zb = z4[m][bj][2 * n + 1];
;                         const float o0 = bflo(ya) * sigmoidf_(a[0]) * bflo(za), o1 = bfhi(ya) * sigmoidf_(a[1]) * bfhi(za);
;                         const float o2 = bflo(yb) * sigmoidf_(a[2]) * bflo(zb), o3 = bfhi(yb) * sigmoidf_(a[3]) * bfhi(zb);
;                         w[2 * n] = pk2(o0, o1); w[2 * n + 1] = pk2(o2, o3);
;                     }
;                     *(u32x4*)(MIXED + (size_t)row * 1024 + 512 + col) = (u32x4){w[0], w[1], w[2], w[3]};
;                 }
	v_mul_f32_e32 v131, 0xbfb8aa3b, v131
	v_pk_mul_f32 v[148:149], v[148:149], v[152:153]
	v_rcp_f32_e32 v134, v134
	v_rcp_f32_e32 v135, v135
	v_exp_f32_e32 v130, v130
	v_exp_f32_e32 v131, v131
	v_pk_add_f32 v[132:133], v[132:133], v[68:69]
	v_cvt_pk_bf16_f32 v152, v146, v147
	v_cvt_pk_bf16_f32 v153, v148, v149
	v_lshl_add_u64 v[146:147], s[78:79], 0, v[226:227]
	v_lshlrev_b32_e32 v148, 1, v199
	v_mov_b32_e32 v149, v203
	v_add_f32_e32 v136, 1.0, v136
	v_add_f32_e32 v137, 1.0, v137
	v_mul_f32_e32 v132, 0xbfb8aa3b, v132
	v_mul_f32_e32 v133, 0xbfb8aa3b, v133
	v_lshl_add_u64 v[146:147], v[146:147], 0, v[148:149]
	v_rcp_f32_e32 v136, v136
	v_rcp_f32_e32 v137, v137
	v_exp_f32_e32 v132, v132
	v_exp_f32_e32 v133, v133
	global_store_dwordx4 v[146:147], v[150:153], off offset:1024
	v_add_u32_e32 v236, 0x10000, v202
	v_mov_b32_e32 v237, v203
	v_lshlrev_b64 v[236:237], 1, v[236:237]
	v_lshl_add_u64 v[238:239], s[4:5], 0, v[236:237]
	v_lshl_add_u64 v[236:237], s[14:15], 0, v[236:237]
	global_load_dwordx4 v[208:211], v[238:239], off
	global_load_dwordx4 v[214:217], v[236:237], off
	v_pk_add_f32 v[126:127], v[126:127], v[78:79]
	v_add_f32_e32 v130, 1.0, v130
	v_lshlrev_b32_e32 v150, 16, v218
	v_and_b32_e32 v151, 0xffff0000, v218
	v_pk_mul_f32 v[134:135], v[134:135], v[150:151]
	v_lshlrev_b32_e32 v150, 16, v222
	v_and_b32_e32 v151, 0xffff0000, v222
	v_add_f32_e32 v131, 1.0, v131
	v_mul_f32_e32 v126, 0xbfb8aa3b, v126
	v_mul_f32_e32 v127, 0xbfb8aa3b, v127
	v_pk_mul_f32 v[134:135], v[134:135], v[150:151]
	v_lshlrev_b32_e32 v150, 16, v219
	v_and_b32_e32 v151, 0xffff0000, v219
	v_rcp_f32_e32 v130, v130
	v_rcp_f32_e32 v131, v131
	v_exp_f32_e32 v126, v126
	v_exp_f32_e32 v127, v127
	v_pk_add_f32 v[128:129], v[128:129], v[80:81]
	v_pk_mul_f32 v[136:137], v[136:137], v[150:151]
	v_lshlrev_b32_e32 v150, 16, v223
	v_and_b32_e32 v151, 0xffff0000, v223
	v_add_f32_e32 v132, 1.0, v132
	v_add_f32_e32 v133, 1.0, v133
	v_mul_f32_e32 v128, 0xbfb8aa3b, v128
	v_mul_f32_e32 v129, 0xbfb8aa3b, v129
	v_pk_mul_f32 v[136:137], v[136:137], v[150:151]
	v_rcp_f32_e32 v132, v132
	v_rcp_f32_e32 v133, v133
	v_exp_f32_e32 v128, v128
	v_exp_f32_e32 v129, v129
	v_cvt_pk_bf16_f32 v134, v134, v135
	v_cvt_pk_bf16_f32 v135, v136, v137
	v_lshlrev_b32_e32 v136, 16, v220
	v_and_b32_e32 v137, 0xffff0000, v220
	v_pk_add_f32 v[122:123], v[122:123], v[70:71]
	v_pk_mul_f32 v[130:131], v[130:131], v[136:137]
	v_lshlrev_b32_e32 v136, 16, v224
	v_and_b32_e32 v137, 0xffff0000, v224
	v_add_f32_e32 v126, 1.0, v126
	v_add_f32_e32 v127, 1.0, v127
	v_mul_f32_e32 v122, 0xbfb8aa3b, v122
	v_mul_f32_e32 v123, 0xbfb8aa3b, v123
	v_pk_mul_f32 v[130:131], v[130:131], v[136:137]
	v_lshlrev_b32_e32 v136, 16, v221
	v_and_b32_e32 v137, 0xffff0000, v221
	v_rcp_f32_e32 v126, v126
	v_rcp_f32_e32 v127, v127
	v_exp_f32_e32 v122, v122
	v_exp_f32_e32 v123, v123
	v_pk_add_f32 v[124:125], v[124:125], v[72:73]
	v_pk_mul_f32 v[132:133], v[132:133], v[136:137]
	v_lshlrev_b32_e32 v136, 16, v225
	v_and_b32_e32 v137, 0xffff0000, v225
	v_add_u32_e32 v236, 0x10020, v202
	v_mov_b32_e32 v237, v203
	v_lshlrev_b64 v[236:237], 1, v[236:237]
	v_lshl_add_u64 v[238:239], s[4:5], 0, v[236:237]
	v_lshl_add_u64 v[236:237], s[14:15], 0, v[236:237]
	global_load_dwordx4 v[218:221], v[238:239], off
	global_load_dwordx4 v[222:225], v[236:237], off
	v_add_f32_e32 v128, 1.0, v128
	v_add_f32_e32 v129, 1.0, v129
	v_mul_f32_e32 v124, 0xbfb8aa3b, v124
	v_mul_f32_e32 v125, 0xbfb8aa3b, v125
	v_pk_mul_f32 v[132:133], v[132:133], v[136:137]
	v_rcp_f32_e32 v128, v128
	v_rcp_f32_e32 v129, v129
	v_exp_f32_e32 v124, v124
	v_exp_f32_e32 v125, v125
	v_cvt_pk_bf16_f32 v137, v132, v133
	v_lshlrev_b32_e32 v132, 16, v190
	v_and_b32_e32 v133, 0xffff0000, v190
	v_pk_add_f32 v[118:119], v[118:119], v[74:75]
	v_pk_mul_f32 v[126:127], v[126:127], v[132:133]
	v_lshlrev_b32_e32 v132, 16, v186
	v_and_b32_e32 v133, 0xffff0000, v186
	v_add_f32_e32 v122, 1.0, v122
	v_add_f32_e32 v123, 1.0, v123
	v_mul_f32_e32 v118, 0xbfb8aa3b, v118
	v_mul_f32_e32 v119, 0xbfb8aa3b, v119
	v_pk_mul_f32 v[126:127], v[126:127], v[132:133]
	v_lshlrev_b32_e32 v132, 16, v191
	v_and_b32_e32 v133, 0xffff0000, v191
	v_rcp_f32_e32 v122, v122
	v_rcp_f32_e32 v123, v123
	v_exp_f32_e32 v118, v118
	v_exp_f32_e32 v119, v119
	v_pk_add_f32 v[120:121], v[120:121], v[76:77]
	v_pk_mul_f32 v[128:129], v[128:129], v[132:133]
	v_lshlrev_b32_e32 v132, 16, v187
	v_and_b32_e32 v133, 0xffff0000, v187
	v_add_f32_e32 v124, 1.0, v124
	v_add_f32_e32 v125, 1.0, v125
	v_mul_f32_e32 v120, 0xbfb8aa3b, v120
	v_mul_f32_e32 v121, 0xbfb8aa3b, v121
	v_pk_mul_f32 v[128:129], v[128:129], v[132:133]
	v_rcp_f32_e32 v124, v124
	v_rcp_f32_e32 v125, v125
	v_exp_f32_e32 v120, v120
	v_exp_f32_e32 v121, v121
	v_cvt_pk_bf16_f32 v126, v126, v127
	v_cvt_pk_bf16_f32 v127, v128, v129
	v_lshlrev_b32_e32 v128, 16, v192
	v_and_b32_e32 v129, 0xffff0000, v192
	v_pk_add_f32 v[114:115], v[114:115], v[66:67]
	v_pk_mul_f32 v[122:123], v[122:123], v[128:129]
	v_lshlrev_b32_e32 v128, 16, v188
	v_and_b32_e32 v129, 0xffff0000, v188
	v_add_f32_e32 v118, 1.0, v118
	v_add_f32_e32 v119, 1.0, v119
	v_mul_f32_e32 v114, 0xbfb8aa3b, v114
	v_mul_f32_e32 v115, 0xbfb8aa3b, v115
	v_pk_mul_f32 v[122:123], v[122:123], v[128:129]
	v_lshlrev_b32_e32 v128, 16, v193
	v_and_b32_e32 v129, 0xffff0000, v193
	v_rcp_f32_e32 v118, v118
	v_rcp_f32_e32 v119, v119
	v_exp_f32_e32 v114, v114
	v_exp_f32_e32 v115, v115
	v_pk_add_f32 v[116:117], v[116:117], v[68:69]
	v_pk_mul_f32 v[124:125], v[124:125], v[128:129]
	v_lshlrev_b32_e32 v128, 16, v189
	v_and_b32_e32 v129, 0xffff0000, v189
	v_add_u32_e32 v236, 0x12000, v202
	v_mov_b32_e32 v237, v203
	v_lshlrev_b64 v[236:237], 1, v[236:237]
; __device__ __forceinline__ unsigned pk2(float lo, float hi) { const f32x2c_t v = {lo, hi}; return __builtin_bit_cast(unsigned, __builtin_convertvector(v, bf16x2c_t)); }
; __device__ __forceinline__ float bflo(unsigned w) { return __uint_as_float(w << 16); }
; __device__ __forceinline__ float bfhi(unsigned w) { return __uint_as_float(w & 0xffff0000u); }
; __device__ __forceinline__ float sigmoidf_(float v) { return __builtin_amdgcn_rcpf(1.f + __expf(-v)); }
;     __device__ __forceinline__ void operator()(const f32x4 (&acc)[2][2][4][2], const Unit& u, int wr, int wc, int fr, int fq) const {
;     ...
;         for (int ai = 0; ai < 2; ++ai) {
;             u32x4 y4[4][2], z4[4][2];
; #pragma unroll
;             for (int m = 0; m < 4; ++m) {
;                 const int row = 256 * u.pm + 128 * ai + 64 * wr + 16 * m + fr;
; #pragma unroll
;                 for (int bj = 0; bj < 2; ++bj) {
;                     const unsigned off = (unsigned)row * 512u + (unsigned)(256 * u.pn + 64 * wc + 32 * bj + 8 * fq);
;                     y4[m][bj] = *(const u32x4*)(YG + off); z4[m][bj] = *(const u32x4*)(SZS + off);
;                 }
;             }
; #pragma unroll
;             for (int m = 0; m < 4; ++m) {
;                 const int row = 256 * u.pm + 128 * ai + 64 * wr + 16 * m + fr;
; #pragma unroll
;                 for (int bj = 0; bj < 2; ++bj) {
;                     const int col = 256 * u.pn + 64 * wc + 32 * bj + 8 * fq;
;                     unsigned w[4];
; #pragma unroll
;                     for (int n = 0; n < 2; ++n) {
;                         const f32x4 a = acc[ai][bj][m][n] + bias[bj][n];
;                         const unsigned ya = y4[m][bj][2 * n], yb = y4[m][bj][2 * n + 1], za = z4[m][bj][2 * n], zb = z4[m][bj][2 * n + 1];
;                         const float o0 = bflo(ya) * sigmoidf_(a[0]) * bflo(za), o1 = bfhi(ya) * sigmoidf_(a[1]) * bfhi(za);
;                         const float o2 = bflo(yb) * sigmoidf_(a[2]) * bflo(zb), o3 = bfhi(yb) * sigmoidf_(a[3]) * bfhi(zb);
;                         w[2 * n] = pk2(o0, o1); w[2 * n + 1] = pk2(o2, o3);
;                     }
;                     *(u32x4*)(MIXED + (size_t)row * 1024 + 512 + col) = (u32x4){w[0], w[1], w[2], w[3]};
;                 }
	v_lshl_add_u64 v[238:239], s[4:5], 0, v[236:237]
	v_lshl_add_u64 v[236:237], s[14:15], 0, v[236:237]
	global_load_dwordx4 v[190:193], v[238:239], off
	global_load_dwordx4 v[186:189], v[236:237], off
	v_add_f32_e32 v120, 1.0, v120
	v_add_f32_e32 v121, 1.0, v121
	v_mul_f32_e32 v116, 0xbfb8aa3b, v116
	v_mul_f32_e32 v117, 0xbfb8aa3b, v117
	v_pk_mul_f32 v[124:125], v[124:125], v[128:129]
	v_rcp_f32_e32 v120, v120
	v_rcp_f32_e32 v121, v121
	v_exp_f32_e32 v116, v116
	v_exp_f32_e32 v117, v117
	v_cvt_pk_bf16_f32 v129, v124, v125
	v_lshlrev_b32_e32 v124, 16, v182
	v_and_b32_e32 v125, 0xffff0000, v182
	v_pk_add_f32 v[110:111], v[110:111], v[78:79]
	v_pk_mul_f32 v[118:119], v[118:119], v[124:125]
	v_lshlrev_b32_e32 v124, 16, v178
	v_and_b32_e32 v125, 0xffff0000, v178
	v_add_f32_e32 v114, 1.0, v114
	v_add_f32_e32 v115, 1.0, v115
	v_mul_f32_e32 v110, 0xbfb8aa3b, v110
	v_mul_f32_e32 v111, 0xbfb8aa3b, v111
	v_pk_mul_f32 v[118:119], v[118:119], v[124:125]
	v_lshlrev_b32_e32 v124, 16, v183
	v_and_b32_e32 v125, 0xffff0000, v183
	v_rcp_f32_e32 v114, v114
	v_rcp_f32_e32 v115, v115
	v_exp_f32_e32 v110, v110
	v_exp_f32_e32 v111, v111
	v_pk_add_f32 v[112:113], v[112:113], v[80:81]
	v_pk_mul_f32 v[120:121], v[120:121], v[124:125]
	v_lshlrev_b32_e32 v124, 16, v179
	v_and_b32_e32 v125, 0xffff0000, v179
	v_add_f32_e32 v116, 1.0, v116
	v_add_f32_e32 v117, 1.0, v117
	v_mul_f32_e32 v112, 0xbfb8aa3b, v112
	v_mul_f32_e32 v113, 0xbfb8aa3b, v113
	v_pk_mul_f32 v[120:121], v[120:121], v[124:125]
	v_rcp_f32_e32 v116, v116
	v_rcp_f32_e32 v117, v117
	v_exp_f32_e32 v112, v112
	v_exp_f32_e32 v113, v113
	v_cvt_pk_bf16_f32 v118, v118, v119
	v_cvt_pk_bf16_f32 v119, v120, v121
	v_lshlrev_b32_e32 v120, 16, v184
	v_and_b32_e32 v121, 0xffff0000, v184
	v_pk_add_f32 v[106:107], v[106:107], v[70:71]
	v_pk_mul_f32 v[114:115], v[114:115], v[120:121]
	v_lshlrev_b32_e32 v120, 16, v180
	v_and_b32_e32 v121, 0xffff0000, v180
	v_add_f32_e32 v110, 1.0, v110
	v_add_f32_e32 v111, 1.0, v111
	v_mul_f32_e32 v106, 0xbfb8aa3b, v106
	v_mul_f32_e32 v107, 0xbfb8aa3b, v107
	v_pk_mul_f32 v[114:115], v[114:115], v[120:121]
	v_lshlrev_b32_e32 v120, 16, v185
	v_and_b32_e32 v121, 0xffff0000, v185
	v_rcp_f32_e32 v110, v110
	v_rcp_f32_e32 v111, v111
	v_exp_f32_e32 v106, v106
	v_exp_f32_e32 v107, v107
	v_pk_add_f32 v[108:109], v[108:109], v[72:73]
	v_pk_mul_f32 v[116:117], v[116:117], v[120:121]
	v_lshlrev_b32_e32 v120, 16, v181
	v_and_b32_e32 v121, 0xffff0000, v181
	v_add_u32_e32 v236, 0x12020, v202
	v_mov_b32_e32 v237, v203
	v_lshlrev_b64 v[236:237], 1, v[236:237]
	v_lshl_add_u64 v[238:239], s[4:5], 0, v[236:237]
	v_lshl_add_u64 v[236:237], s[14:15], 0, v[236:237]
	global_load_dwordx4 v[182:185], v[238:239], off
	global_load_dwordx4 v[178:181], v[236:237], off
	v_add_f32_e32 v112, 1.0, v112
	v_add_f32_e32 v113, 1.0, v113
	v_mul_f32_e32 v108, 0xbfb8aa3b, v108
	v_mul_f32_e32 v109, 0xbfb8aa3b, v109
	v_pk_mul_f32 v[116:117], v[116:117], v[120:121]
	v_rcp_f32_e32 v112, v112
	v_rcp_f32_e32 v113, v113
	v_exp_f32_e32 v108, v108
	v_exp_f32_e32 v109, v109
	v_cvt_pk_bf16_f32 v121, v116, v117
	v_lshlrev_b32_e32 v116, 16, v174
	v_and_b32_e32 v117, 0xffff0000, v174
	v_pk_add_f32 v[102:103], v[102:103], v[74:75]
	v_pk_mul_f32 v[110:111], v[110:111], v[116:117]
	v_lshlrev_b32_e32 v116, 16, v170
	v_and_b32_e32 v117, 0xffff0000, v170
	v_add_f32_e32 v106, 1.0, v106
	v_add_f32_e32 v107, 1.0, v107
	v_mul_f32_e32 v102, 0xbfb8aa3b, v102
	v_mul_f32_e32 v103, 0xbfb8aa3b, v103
	v_pk_mul_f32 v[110:111], v[110:111], v[116:117]
	v_lshlrev_b32_e32 v116, 16, v175
	v_and_b32_e32 v117, 0xffff0000, v175
	v_rcp_f32_e32 v106, v106
	v_rcp_f32_e32 v107, v107
	v_exp_f32_e32 v102, v102
	v_exp_f32_e32 v103, v103
	v_pk_add_f32 v[104:105], v[104:105], v[76:77]
	v_pk_mul_f32 v[112:113], v[112:113], v[116:117]
	v_lshlrev_b32_e32 v116, 16, v171
	v_and_b32_e32 v117, 0xffff0000, v171
	v_add_f32_e32 v108, 1.0, v108
	v_add_f32_e32 v109, 1.0, v109
	v_mul_f32_e32 v104, 0xbfb8aa3b, v104
	v_mul_f32_e32 v105, 0xbfb8aa3b, v105
	v_pk_mul_f32 v[112:113], v[112:113], v[116:117]
	v_rcp_f32_e32 v108, v108
	v_rcp_f32_e32 v109, v109
	v_exp_f32_e32 v104, v104
	v_exp_f32_e32 v105, v105
	v_cvt_pk_bf16_f32 v110, v110, v111
	v_cvt_pk_bf16_f32 v111, v112, v113
	v_lshlrev_b32_e32 v112, 16, v176
	v_and_b32_e32 v113, 0xffff0000, v176
	v_pk_add_f32 v[98:99], v[98:99], v[66:67]
	v_pk_mul_f32 v[106:107], v[106:107], v[112:113]
	v_lshlrev_b32_e32 v112, 16, v172
	v_and_b32_e32 v113, 0xffff0000, v172
	v_add_f32_e32 v102, 1.0, v102
	v_add_f32_e32 v103, 1.0, v103
	v_mul_f32_e32 v98, 0xbfb8aa3b, v98
	v_mul_f32_e32 v99, 0xbfb8aa3b, v99
	v_pk_mul_f32 v[106:107], v[106:107], v[112:113]
	v_lshlrev_b32_e32 v112, 16, v177
	v_and_b32_e32 v113, 0xffff0000, v177
	v_rcp_f32_e32 v102, v102
	v_rcp_f32_e32 v103, v103
	v_exp_f32_e32 v98, v98
	v_exp_f32_e32 v99, v99
	v_pk_add_f32 v[100:101], v[100:101], v[68:69]
	v_pk_mul_f32 v[108:109], v[108:109], v[112:113]
	v_lshlrev_b32_e32 v112, 16, v173
	v_and_b32_e32 v113, 0xffff0000, v173
	v_add_u32_e32 v236, 0x14000, v202
	v_mov_b32_e32 v237, v203
	v_lshlrev_b64 v[236:237], 1, v[236:237]
	v_lshl_add_u64 v[238:239], s[4:5], 0, v[236:237]
	v_lshl_add_u64 v[236:237], s[14:15], 0, v[236:237]
	global_load_dwordx4 v[174:177], v[238:239], off
	global_load_dwordx4 v[170:173], v[236:237], off
	v_add_f32_e32 v104, 1.0, v104
	v_add_f32_e32 v105, 1.0, v105
	v_mul_f32_e32 v100, 0xbfb8aa3b, v100
	v_mul_f32_e32 v101, 0xbfb8aa3b, v101
	v_pk_mul_f32 v[108:109], v[108:109], v[112:113]
	v_rcp_f32_e32 v104, v104
	v_rcp_f32_e32 v105, v105
	v_exp_f32_e32 v100, v100
	v_exp_f32_e32 v101, v101
	v_cvt_pk_bf16_f32 v113, v108, v109
	v_lshlrev_b32_e32 v108, 16, v166
	v_and_b32_e32 v109, 0xffff0000, v166
; __device__ __forceinline__ unsigned pk2(float lo, float hi) { const f32x2c_t v = {lo, hi}; return __builtin_bit_cast(unsigned, __builtin_convertvector(v, bf16x2c_t)); }
; __device__ __forceinline__ float bflo(unsigned w) { return __uint_as_float(w << 16); }
; __device__ __forceinline__ float bfhi(unsigned w) { return __uint_as_float(w & 0xffff0000u); }
; __device__ __forceinline__ float sigmoidf_(float v) { return __builtin_amdgcn_rcpf(1.f + __expf(-v)); }
;     __device__ __forceinline__ void operator()(const f32x4 (&acc)[2][2][4][2], const Unit& u, int wr, int wc, int fr, int fq) const {
;     ...
;         for (int ai = 0; ai < 2; ++ai) {
;             u32x4 y4[4][2], z4[4][2];
; #pragma unroll
;             for (int m = 0; m < 4; ++m) {
;                 const int row = 256 * u.pm + 128 * ai + 64 * wr + 16 * m + fr;
; #pragma unroll
;                 for (int bj = 0; bj < 2; ++bj) {
;                     const unsigned off = (unsigned)row * 512u + (unsigned)(256 * u.pn + 64 * wc + 32 * bj + 8 * fq);
;                     y4[m][bj] = *(const u32x4*)(YG + off); z4[m][bj] = *(const u32x4*)(SZS + off);
;                 }
;             }
; #pragma unroll
;             for (int m = 0; m < 4; ++m) {
;                 const int row = 256 * u.pm + 128 * ai + 64 * wr + 16 * m + fr;
; #pragma unroll
;                 for (int bj = 0; bj < 2; ++bj) {
;                     const int col = 256 * u.pn + 64 * wc + 32 * bj + 8 * fq;
;                     unsigned w[4];
; #pragma unroll
;                     for (int n = 0; n < 2; ++n) {
;                         const f32x4 a = acc[ai][bj][m][n] + bias[bj][n];
;                         const unsigned ya = y4[m][bj][2 * n], yb = y4[m][bj][2 * n + 1], za = z4[m][bj][2 * n], zb = z4[m][bj][2 * n + 1];
;                         const float o0 = bflo(ya) * sigmoidf_(a[0]) * bflo(za), o1 = bfhi(ya) * sigmoidf_(a[1]) * bfhi(za);
;                         const float o2 = bflo(yb) * sigmoidf_(a[2]) * bflo(zb), o3 = bfhi(yb) * sigmoidf_(a[3]) * bfhi(zb);
;                         w[2 * n] = pk2(o0, o1); w[2 * n + 1] = pk2(o2, o3);
;                     }
;                     *(u32x4*)(MIXED + (size_t)row * 1024 + 512 + col) = (u32x4){w[0], w[1], w[2], w[3]};
;                 }
	v_pk_add_f32 v[94:95], v[94:95], v[78:79]
	v_pk_mul_f32 v[102:103], v[102:103], v[108:109]
	v_lshlrev_b32_e32 v108, 16, v162
	v_and_b32_e32 v109, 0xffff0000, v162
	v_add_f32_e32 v98, 1.0, v98
	v_add_f32_e32 v99, 1.0, v99
	v_mul_f32_e32 v94, 0xbfb8aa3b, v94
	v_mul_f32_e32 v95, 0xbfb8aa3b, v95
	v_pk_mul_f32 v[102:103], v[102:103], v[108:109]
	v_lshlrev_b32_e32 v108, 16, v167
	v_and_b32_e32 v109, 0xffff0000, v167
	v_rcp_f32_e32 v98, v98
	v_rcp_f32_e32 v99, v99
	v_exp_f32_e32 v94, v94
	v_exp_f32_e32 v95, v95
	v_pk_add_f32 v[96:97], v[96:97], v[80:81]
	v_pk_mul_f32 v[104:105], v[104:105], v[108:109]
	v_lshlrev_b32_e32 v108, 16, v163
	v_and_b32_e32 v109, 0xffff0000, v163
	v_add_f32_e32 v100, 1.0, v100
	v_add_f32_e32 v101, 1.0, v101
	v_mul_f32_e32 v96, 0xbfb8aa3b, v96
	v_mul_f32_e32 v97, 0xbfb8aa3b, v97
	v_pk_mul_f32 v[104:105], v[104:105], v[108:109]
	v_rcp_f32_e32 v100, v100
	v_rcp_f32_e32 v101, v101
	v_exp_f32_e32 v96, v96
	v_exp_f32_e32 v97, v97
	v_cvt_pk_bf16_f32 v102, v102, v103
	v_cvt_pk_bf16_f32 v103, v104, v105
	v_lshlrev_b32_e32 v104, 16, v168
	v_and_b32_e32 v105, 0xffff0000, v168
	v_pk_add_f32 v[90:91], v[90:91], v[70:71]
	v_pk_mul_f32 v[98:99], v[98:99], v[104:105]
	v_lshlrev_b32_e32 v104, 16, v164
	v_and_b32_e32 v105, 0xffff0000, v164
	v_add_f32_e32 v94, 1.0, v94
	v_add_f32_e32 v95, 1.0, v95
	v_mul_f32_e32 v90, 0xbfb8aa3b, v90
	v_mul_f32_e32 v91, 0xbfb8aa3b, v91
	v_pk_mul_f32 v[98:99], v[98:99], v[104:105]
	v_lshlrev_b32_e32 v104, 16, v169
	v_and_b32_e32 v105, 0xffff0000, v169
	v_rcp_f32_e32 v94, v94
	v_rcp_f32_e32 v95, v95
	v_exp_f32_e32 v90, v90
	v_exp_f32_e32 v91, v91
	v_pk_add_f32 v[92:93], v[92:93], v[72:73]
	v_pk_mul_f32 v[100:101], v[100:101], v[104:105]
	v_lshlrev_b32_e32 v104, 16, v165
	v_and_b32_e32 v105, 0xffff0000, v165
	v_add_u32_e32 v236, 0x14020, v202
	v_mov_b32_e32 v237, v203
	v_lshlrev_b64 v[236:237], 1, v[236:237]
	v_lshl_add_u64 v[238:239], s[4:5], 0, v[236:237]
	v_lshl_add_u64 v[236:237], s[14:15], 0, v[236:237]
	global_load_dwordx4 v[166:169], v[238:239], off
	global_load_dwordx4 v[162:165], v[236:237], off
	v_add_f32_e32 v96, 1.0, v96
	v_add_f32_e32 v97, 1.0, v97
	v_mul_f32_e32 v92, 0xbfb8aa3b, v92
	v_mul_f32_e32 v93, 0xbfb8aa3b, v93
	v_pk_mul_f32 v[100:101], v[100:101], v[104:105]
	v_rcp_f32_e32 v96, v96
	v_rcp_f32_e32 v97, v97
	v_exp_f32_e32 v92, v92
	v_exp_f32_e32 v93, v93
	v_cvt_pk_bf16_f32 v105, v100, v101
	v_lshlrev_b32_e32 v100, 16, v158
	v_and_b32_e32 v101, 0xffff0000, v158
	v_pk_add_f32 v[86:87], v[86:87], v[74:75]
	v_pk_mul_f32 v[94:95], v[94:95], v[100:101]
	v_lshlrev_b32_e32 v100, 16, v154
	v_and_b32_e32 v101, 0xffff0000, v154
	v_add_f32_e32 v90, 1.0, v90
	v_add_f32_e32 v91, 1.0, v91
	v_mul_f32_e32 v86, 0xbfb8aa3b, v86
	v_mul_f32_e32 v87, 0xbfb8aa3b, v87
	v_pk_mul_f32 v[94:95], v[94:95], v[100:101]
	v_lshlrev_b32_e32 v100, 16, v159
	v_and_b32_e32 v101, 0xffff0000, v159
	v_rcp_f32_e32 v90, v90
	v_rcp_f32_e32 v91, v91
	v_exp_f32_e32 v86, v86
	v_exp_f32_e32 v87, v87
	v_pk_add_f32 v[88:89], v[88:89], v[76:77]
	v_pk_mul_f32 v[96:97], v[96:97], v[100:101]
	v_lshlrev_b32_e32 v100, 16, v155
	v_and_b32_e32 v101, 0xffff0000, v155
	v_add_f32_e32 v92, 1.0, v92
	v_add_f32_e32 v93, 1.0, v93
	v_mul_f32_e32 v88, 0xbfb8aa3b, v88
	v_mul_f32_e32 v89, 0xbfb8aa3b, v89
	v_pk_mul_f32 v[96:97], v[96:97], v[100:101]
	v_rcp_f32_e32 v92, v92
	v_rcp_f32_e32 v93, v93
	v_exp_f32_e32 v88, v88
	v_exp_f32_e32 v89, v89
	v_cvt_pk_bf16_f32 v94, v94, v95
	v_cvt_pk_bf16_f32 v95, v96, v97
	v_lshlrev_b32_e32 v96, 16, v160
	v_and_b32_e32 v97, 0xffff0000, v160
	v_pk_add_f32 v[82:83], v[82:83], v[66:67]
	v_pk_mul_f32 v[90:91], v[90:91], v[96:97]
	v_lshlrev_b32_e32 v96, 16, v156
	v_and_b32_e32 v97, 0xffff0000, v156
	v_add_f32_e32 v86, 1.0, v86
	v_add_f32_e32 v87, 1.0, v87
	v_mul_f32_e32 v82, 0xbfb8aa3b, v82
	v_mul_f32_e32 v83, 0xbfb8aa3b, v83
	v_pk_mul_f32 v[90:91], v[90:91], v[96:97]
	v_lshlrev_b32_e32 v96, 16, v161
	v_and_b32_e32 v97, 0xffff0000, v161
	v_rcp_f32_e32 v86, v86
	v_rcp_f32_e32 v87, v87
	v_exp_f32_e32 v82, v82
	v_exp_f32_e32 v83, v83
	v_pk_add_f32 v[84:85], v[84:85], v[68:69]
	v_pk_mul_f32 v[92:93], v[92:93], v[96:97]
	v_lshlrev_b32_e32 v96, 16, v157
	v_and_b32_e32 v97, 0xffff0000, v157
	v_add_u32_e32 v236, 0x16000, v202
	v_mov_b32_e32 v237, v203
	v_lshlrev_b64 v[236:237], 1, v[236:237]
	v_lshl_add_u64 v[238:239], s[4:5], 0, v[236:237]
	v_lshl_add_u64 v[236:237], s[14:15], 0, v[236:237]
	global_load_dwordx4 v[158:161], v[238:239], off
	global_load_dwordx4 v[154:157], v[236:237], off
	v_add_f32_e32 v88, 1.0, v88
	v_add_f32_e32 v89, 1.0, v89
	v_mul_f32_e32 v84, 0xbfb8aa3b, v84
	v_mul_f32_e32 v85, 0xbfb8aa3b, v85
	v_pk_mul_f32 v[92:93], v[92:93], v[96:97]
	v_rcp_f32_e32 v88, v88
	v_rcp_f32_e32 v89, v89
	v_exp_f32_e32 v84, v84
	v_exp_f32_e32 v85, v85
	v_cvt_pk_bf16_f32 v97, v92, v93
	v_lshlrev_b32_e32 v92, 16, v142
	v_and_b32_e32 v93, 0xffff0000, v142
	v_pk_mul_f32 v[86:87], v[86:87], v[92:93]
	v_lshlrev_b32_e32 v92, 16, v138
	v_and_b32_e32 v93, 0xffff0000, v138
	v_add_f32_e32 v82, 1.0, v82
	v_add_f32_e32 v83, 1.0, v83
	v_pk_mul_f32 v[86:87], v[86:87], v[92:93]
	v_lshlrev_b32_e32 v92, 16, v143
	v_and_b32_e32 v93, 0xffff0000, v143
	v_rcp_f32_e32 v82, v82
	v_rcp_f32_e32 v83, v83
	v_pk_mul_f32 v[88:89], v[88:89], v[92:93]
	v_lshlrev_b32_e32 v92, 16, v139
	v_and_b32_e32 v93, 0xffff0000, v139
	v_add_f32_e32 v84, 1.0, v84
	v_add_f32_e32 v85, 1.0, v85
	v_pk_mul_f32 v[88:89], v[88:89], v[92:93]
	v_rcp_f32_e32 v84, v84
	v_rcp_f32_e32 v85, v85
	v_cvt_pk_bf16_f32 v86, v86, v87
	v_cvt_pk_bf16_f32 v87, v88, v89
	v_lshlrev_b32_e32 v88, 16, v144
	v_and_b32_e32 v89, 0xffff0000, v144
	v_cvt_pk_bf16_f32 v136, v130, v131
	v_or_b32_e32 v130, 16, v204
; __device__ __forceinline__ unsigned pk2(float lo, float hi) { const f32x2c_t v = {lo, hi}; return __builtin_bit_cast(unsigned, __builtin_convertvector(v, bf16x2c_t)); }
; __device__ __forceinline__ float bflo(unsigned w) { return __uint_as_float(w << 16); }
; __device__ __forceinline__ float bfhi(unsigned w) { return __uint_as_float(w & 0xffff0000u); }
; __device__ __forceinline__ float sigmoidf_(float v) { return __builtin_amdgcn_rcpf(1.f + __expf(-v)); }
;     __device__ __forceinline__ void operator()(const f32x4 (&acc)[2][2][4][2], const Unit& u, int wr, int wc, int fr, int fq) const {
;     ...
;         for (int ai = 0; ai < 2; ++ai) {
;             u32x4 y4[4][2], z4[4][2];
; #pragma unroll
;             for (int m = 0; m < 4; ++m) {
;                 const int row = 256 * u.pm + 128 * ai + 64 * wr + 16 * m + fr;
; #pragma unroll
;                 for (int bj = 0; bj < 2; ++bj) {
;                     const unsigned off = (unsigned)row * 512u + (unsigned)(256 * u.pn + 64 * wc + 32 * bj + 8 * fq);
;                     y4[m][bj] = *(const u32x4*)(YG + off); z4[m][bj] = *(const u32x4*)(SZS + off);
;                 }
;             }
; #pragma unroll
;             for (int m = 0; m < 4; ++m) {
;                 const int row = 256 * u.pm + 128 * ai + 64 * wr + 16 * m + fr;
; #pragma unroll
;                 for (int bj = 0; bj < 2; ++bj) {
;                     const int col = 256 * u.pn + 64 * wc + 32 * bj + 8 * fq;
;                     unsigned w[4];
; #pragma unroll
;                     for (int n = 0; n < 2; ++n) {
;                         const f32x4 a = acc[ai][bj][m][n] + bias[bj][n];
;                         const unsigned ya = y4[m][bj][2 * n], yb = y4[m][bj][2 * n + 1], za = z4[m][bj][2 * n], zb = z4[m][bj][2 * n + 1];
;                         const float o0 = bflo(ya) * sigmoidf_(a[0]) * bflo(za), o1 = bfhi(ya) * sigmoidf_(a[1]) * bfhi(za);
;                         const float o2 = bflo(yb) * sigmoidf_(a[2]) * bflo(zb), o3 = bfhi(yb) * sigmoidf_(a[3]) * bfhi(zb);
;                         w[2 * n] = pk2(o0, o1); w[2 * n + 1] = pk2(o2, o3);
;                     }
;                     *(u32x4*)(MIXED + (size_t)row * 1024 + 512 + col) = (u32x4){w[0], w[1], w[2], w[3]};
;                 }
	v_cvt_pk_bf16_f32 v120, v114, v115
	v_or_b32_e32 v114, 32, v204
	v_cvt_pk_bf16_f32 v104, v98, v99
	v_or_b32_e32 v98, 48, v204
	v_pk_mul_f32 v[82:83], v[82:83], v[88:89]
	v_lshlrev_b32_e32 v88, 16, v140
	v_and_b32_e32 v89, 0xffff0000, v140
	v_ashrrev_i32_e32 v131, 31, v130
	v_ashrrev_i32_e32 v115, 31, v114
	v_ashrrev_i32_e32 v99, 31, v98
	v_pk_mul_f32 v[82:83], v[82:83], v[88:89]
	v_lshlrev_b32_e32 v88, 16, v145
	v_and_b32_e32 v89, 0xffff0000, v145
	v_lshlrev_b64 v[130:131], 11, v[130:131]
	v_lshlrev_b64 v[114:115], 11, v[114:115]
	v_lshlrev_b64 v[98:99], 11, v[98:99]
	v_pk_mul_f32 v[84:85], v[84:85], v[88:89]
	v_lshlrev_b32_e32 v88, 16, v141
	v_and_b32_e32 v89, 0xffff0000, v141
	v_add_u32_e32 v236, 0x16020, v202
	v_mov_b32_e32 v237, v203
	v_lshlrev_b64 v[236:237], 1, v[236:237]
	v_lshl_add_u64 v[238:239], s[4:5], 0, v[236:237]
	v_lshl_add_u64 v[236:237], s[14:15], 0, v[236:237]
	global_load_dwordx4 v[142:145], v[238:239], off
	global_load_dwordx4 v[138:141], v[236:237], off
	v_cvt_pk_bf16_f32 v128, v122, v123
	v_lshl_add_u64 v[122:123], s[78:79], 0, v[130:131]
	v_cvt_pk_bf16_f32 v112, v106, v107
	v_lshl_add_u64 v[106:107], s[78:79], 0, v[114:115]
	v_cvt_pk_bf16_f32 v96, v90, v91
	v_lshl_add_u64 v[90:91], s[78:79], 0, v[98:99]
	v_pk_mul_f32 v[84:85], v[84:85], v[88:89]
	v_cvt_pk_bf16_f32 v88, v82, v83
	v_lshl_add_u64 v[122:123], v[122:123], 0, v[148:149]
	v_lshl_add_u64 v[106:107], v[106:107], 0, v[148:149]
	v_lshl_add_u64 v[90:91], v[90:91], 0, v[148:149]
	v_cvt_pk_bf16_f32 v89, v84, v85
	global_store_dwordx4 v[146:147], v[134:137], off offset:1088
	global_store_dwordx4 v[122:123], v[126:129], off offset:1024
	global_store_dwordx4 v[122:123], v[118:121], off offset:1088
	global_store_dwordx4 v[106:107], v[110:113], off offset:1024
	global_store_dwordx4 v[106:107], v[102:105], off offset:1088
	global_store_dwordx4 v[90:91], v[94:97], off offset:1024
	global_store_dwordx4 v[90:91], v[86:89], off offset:1088
	v_pk_add_f32 v[62:63], v[62:63], v[78:79]
	v_pk_add_f32 v[64:65], v[64:65], v[80:81]
	v_mul_f32_e32 v62, 0xbfb8aa3b, v62
	v_mul_f32_e32 v63, 0xbfb8aa3b, v63
	v_mul_f32_e32 v64, 0xbfb8aa3b, v64
	v_mul_f32_e32 v65, 0xbfb8aa3b, v65
	v_exp_f32_e32 v62, v62
	v_exp_f32_e32 v63, v63
	v_exp_f32_e32 v64, v64
	v_exp_f32_e32 v65, v65
	v_pk_add_f32 v[58:59], v[58:59], v[70:71]
	v_pk_add_f32 v[60:61], v[60:61], v[72:73]
	v_mul_f32_e32 v58, 0xbfb8aa3b, v58
	v_mul_f32_e32 v59, 0xbfb8aa3b, v59
	v_exp_f32_e32 v58, v58
	v_exp_f32_e32 v59, v59
	v_add_f32_e32 v62, 1.0, v62
	v_add_f32_e32 v63, 1.0, v63
	v_add_f32_e32 v64, 1.0, v64
	v_add_f32_e32 v65, 1.0, v65
	v_mul_f32_e32 v60, 0xbfb8aa3b, v60
	v_mul_f32_e32 v61, 0xbfb8aa3b, v61
	v_rcp_f32_e32 v62, v62
	v_rcp_f32_e32 v63, v63
	v_rcp_f32_e32 v64, v64
	v_rcp_f32_e32 v65, v65
	v_exp_f32_e32 v60, v60
	v_exp_f32_e32 v61, v61
	v_pk_add_f32 v[54:55], v[54:55], v[74:75]
	v_add_f32_e32 v58, 1.0, v58
	v_add_f32_e32 v59, 1.0, v59
	v_mul_f32_e32 v54, 0xbfb8aa3b, v54
	v_mul_f32_e32 v55, 0xbfb8aa3b, v55
	v_rcp_f32_e32 v58, v58
	v_rcp_f32_e32 v59, v59
	v_exp_f32_e32 v54, v54
	s_waitcnt vmcnt(21)
	v_lshlrev_b32_e32 v148, 16, v208
	v_and_b32_e32 v149, 0xffff0000, v208
	v_lshlrev_b32_e32 v208, 16, v209
	v_and_b32_e32 v209, 0xffff0000, v209
	v_exp_f32_e32 v55, v55
	v_pk_add_f32 v[56:57], v[56:57], v[76:77]
	v_pk_mul_f32 v[62:63], v[62:63], v[148:149]
	v_lshlrev_b32_e32 v148, 16, v214
	v_and_b32_e32 v149, 0xffff0000, v214
	v_pk_mul_f32 v[64:65], v[64:65], v[208:209]
	v_lshlrev_b32_e32 v208, 16, v215
	v_and_b32_e32 v209, 0xffff0000, v215
	v_add_f32_e32 v60, 1.0, v60
	v_add_f32_e32 v61, 1.0, v61
	v_mul_f32_e32 v56, 0xbfb8aa3b, v56
	v_mul_f32_e32 v57, 0xbfb8aa3b, v57
	v_pk_mul_f32 v[62:63], v[62:63], v[148:149]
	v_pk_mul_f32 v[64:65], v[64:65], v[208:209]
	v_rcp_f32_e32 v60, v60
	v_rcp_f32_e32 v61, v61
	v_exp_f32_e32 v56, v56
	v_exp_f32_e32 v57, v57
	v_cvt_pk_bf16_f32 v62, v62, v63
	v_cvt_pk_bf16_f32 v63, v64, v65
	v_lshlrev_b32_e32 v64, 16, v210
	v_and_b32_e32 v65, 0xffff0000, v210
	v_pk_add_f32 v[50:51], v[50:51], v[66:67]
	v_pk_mul_f32 v[58:59], v[58:59], v[64:65]
	v_lshlrev_b32_e32 v64, 16, v216
	v_and_b32_e32 v65, 0xffff0000, v216
	v_add_f32_e32 v54, 1.0, v54
	v_add_f32_e32 v55, 1.0, v55
	v_mul_f32_e32 v50, 0xbfb8aa3b, v50
	v_mul_f32_e32 v51, 0xbfb8aa3b, v51
	v_pk_mul_f32 v[58:59], v[58:59], v[64:65]
	v_lshlrev_b32_e32 v64, 16, v211
	v_and_b32_e32 v65, 0xffff0000, v211
	v_rcp_f32_e32 v54, v54
	v_rcp_f32_e32 v55, v55
	v_exp_f32_e32 v50, v50
	v_exp_f32_e32 v51, v51
	v_pk_add_f32 v[52:53], v[52:53], v[68:69]
	v_pk_mul_f32 v[60:61], v[60:61], v[64:65]
	v_lshlrev_b32_e32 v64, 16, v217
	v_and_b32_e32 v65, 0xffff0000, v217
	v_add_f32_e32 v56, 1.0, v56
	v_add_f32_e32 v57, 1.0, v57
	v_mul_f32_e32 v52, 0xbfb8aa3b, v52
	v_mul_f32_e32 v53, 0xbfb8aa3b, v53
	v_pk_mul_f32 v[60:61], v[60:61], v[64:65]
	v_rcp_f32_e32 v56, v56
	v_rcp_f32_e32 v57, v57
	v_exp_f32_e32 v52, v52
	v_exp_f32_e32 v53, v53
	v_pk_add_f32 v[46:47], v[46:47], v[78:79]
	v_cvt_pk_bf16_f32 v65, v60, v61
	s_waitcnt vmcnt(19)
; __device__ __forceinline__ unsigned pk2(float lo, float hi) { const f32x2c_t v = {lo, hi}; return __builtin_bit_cast(unsigned, __builtin_convertvector(v, bf16x2c_t)); }
; __device__ __forceinline__ float bflo(unsigned w) { return __uint_as_float(w << 16); }
; __device__ __forceinline__ float bfhi(unsigned w) { return __uint_as_float(w & 0xffff0000u); }
; __device__ __forceinline__ float sigmoidf_(float v) { return __builtin_amdgcn_rcpf(1.f + __expf(-v)); }
;     __device__ __forceinline__ void operator()(const f32x4 (&acc)[2][2][4][2], const Unit& u, int wr, int wc, int fr, int fq) const {
;     ...
; #pragma unroll
;             for (int m = 0; m < 4; ++m) {
;                 const int row = 256 * u.pm + 128 * ai + 64 * wr + 16 * m + fr;
; #pragma unroll
;                 for (int bj = 0; bj < 2; ++bj) {
;                     const int col = 256 * u.pn + 64 * wc + 32 * bj + 8 * fq;
;                     unsigned w[4];
; #pragma unroll
;                     for (int n = 0; n < 2; ++n) {
;                         const f32x4 a = acc[ai][bj][m][n] + bias[bj][n];
;                         const unsigned ya = y4[m][bj][2 * n], yb = y4[m][bj][2 * n + 1], za = z4[m][bj][2 * n], zb = z4[m][bj][2 * n + 1];
;                         const float o0 = bflo(ya) * sigmoidf_(a[0]) * bflo(za), o1 = bfhi(ya) * sigmoidf_(a[1]) * bfhi(za);
;                         const float o2 = bflo(yb) * sigmoidf_(a[2]) * bflo(zb), o3 = bfhi(yb) * sigmoidf_(a[3]) * bfhi(zb);
;                         w[2 * n] = pk2(o0, o1); w[2 * n + 1] = pk2(o2, o3);
;                     }
;                     *(u32x4*)(MIXED + (size_t)row * 1024 + 512 + col) = (u32x4){w[0], w[1], w[2], w[3]};
;                 }
	v_lshlrev_b32_e32 v60, 16, v218
	v_and_b32_e32 v61, 0xffff0000, v218
	v_mul_f32_e32 v46, 0xbfb8aa3b, v46
	v_mul_f32_e32 v47, 0xbfb8aa3b, v47
	v_pk_mul_f32 v[54:55], v[54:55], v[60:61]
	v_lshlrev_b32_e32 v60, 16, v222
	v_and_b32_e32 v61, 0xffff0000, v222
	v_add_f32_e32 v50, 1.0, v50
	v_add_f32_e32 v51, 1.0, v51
	v_exp_f32_e32 v46, v46
	v_exp_f32_e32 v47, v47
	v_pk_add_f32 v[48:49], v[48:49], v[80:81]
	v_pk_mul_f32 v[54:55], v[54:55], v[60:61]
	v_lshlrev_b32_e32 v60, 16, v219
	v_and_b32_e32 v61, 0xffff0000, v219
	v_rcp_f32_e32 v50, v50
	v_rcp_f32_e32 v51, v51
	v_mul_f32_e32 v48, 0xbfb8aa3b, v48
	v_mul_f32_e32 v49, 0xbfb8aa3b, v49
	v_pk_mul_f32 v[56:57], v[56:57], v[60:61]
	v_lshlrev_b32_e32 v60, 16, v223
	v_and_b32_e32 v61, 0xffff0000, v223
	v_add_f32_e32 v52, 1.0, v52
	v_add_f32_e32 v53, 1.0, v53
	v_exp_f32_e32 v48, v48
	v_exp_f32_e32 v49, v49
	v_pk_mul_f32 v[56:57], v[56:57], v[60:61]
	v_rcp_f32_e32 v52, v52
	v_rcp_f32_e32 v53, v53
	v_pk_add_f32 v[42:43], v[42:43], v[70:71]
	v_cvt_pk_bf16_f32 v54, v54, v55
	v_cvt_pk_bf16_f32 v55, v56, v57
	v_lshlrev_b32_e32 v56, 16, v220
	v_and_b32_e32 v57, 0xffff0000, v220
	v_add_f32_e32 v46, 1.0, v46
	v_add_f32_e32 v47, 1.0, v47
	v_mul_f32_e32 v42, 0xbfb8aa3b, v42
	v_mul_f32_e32 v43, 0xbfb8aa3b, v43
	v_pk_mul_f32 v[50:51], v[50:51], v[56:57]
	v_lshlrev_b32_e32 v56, 16, v224
	v_and_b32_e32 v57, 0xffff0000, v224
	v_rcp_f32_e32 v46, v46
	v_rcp_f32_e32 v47, v47
	v_exp_f32_e32 v42, v42
	v_exp_f32_e32 v43, v43
	v_pk_add_f32 v[44:45], v[44:45], v[72:73]
	v_pk_mul_f32 v[50:51], v[50:51], v[56:57]
	v_lshlrev_b32_e32 v56, 16, v221
	v_and_b32_e32 v57, 0xffff0000, v221
	v_add_f32_e32 v48, 1.0, v48
	v_add_f32_e32 v49, 1.0, v49
	v_mul_f32_e32 v44, 0xbfb8aa3b, v44
	v_mul_f32_e32 v45, 0xbfb8aa3b, v45
	v_pk_mul_f32 v[52:53], v[52:53], v[56:57]
	v_lshlrev_b32_e32 v56, 16, v225
	v_and_b32_e32 v57, 0xffff0000, v225
	v_rcp_f32_e32 v48, v48
	v_rcp_f32_e32 v49, v49
	v_exp_f32_e32 v44, v44
	v_exp_f32_e32 v45, v45
	v_pk_mul_f32 v[52:53], v[52:53], v[56:57]
	v_cvt_pk_bf16_f32 v56, v50, v51
	s_waitcnt vmcnt(17)
	v_lshlrev_b32_e32 v50, 16, v190
	v_and_b32_e32 v51, 0xffff0000, v190
	v_pk_add_f32 v[38:39], v[38:39], v[74:75]
	v_pk_mul_f32 v[46:47], v[46:47], v[50:51]
	v_lshlrev_b32_e32 v50, 16, v186
	v_and_b32_e32 v51, 0xffff0000, v186
	v_add_f32_e32 v42, 1.0, v42
	v_add_f32_e32 v43, 1.0, v43
	v_mul_f32_e32 v38, 0xbfb8aa3b, v38
	v_mul_f32_e32 v39, 0xbfb8aa3b, v39
	v_pk_mul_f32 v[46:47], v[46:47], v[50:51]
	v_lshlrev_b32_e32 v50, 16, v191
	v_and_b32_e32 v51, 0xffff0000, v191
	v_rcp_f32_e32 v42, v42
	v_rcp_f32_e32 v43, v43
	v_exp_f32_e32 v38, v38
	v_exp_f32_e32 v39, v39
	v_pk_add_f32 v[40:41], v[40:41], v[76:77]
	v_pk_mul_f32 v[48:49], v[48:49], v[50:51]
	v_lshlrev_b32_e32 v50, 16, v187
	v_and_b32_e32 v51, 0xffff0000, v187
	v_add_f32_e32 v44, 1.0, v44
	v_add_f32_e32 v45, 1.0, v45
	v_mul_f32_e32 v40, 0xbfb8aa3b, v40
	v_mul_f32_e32 v41, 0xbfb8aa3b, v41
	v_pk_mul_f32 v[48:49], v[48:49], v[50:51]
	v_rcp_f32_e32 v44, v44
	v_rcp_f32_e32 v45, v45
	v_exp_f32_e32 v40, v40
	v_exp_f32_e32 v41, v41
	v_cvt_pk_bf16_f32 v46, v46, v47
	v_cvt_pk_bf16_f32 v47, v48, v49
	v_lshlrev_b32_e32 v48, 16, v192
	v_and_b32_e32 v49, 0xffff0000, v192
	v_pk_add_f32 v[34:35], v[34:35], v[66:67]
	v_pk_mul_f32 v[42:43], v[42:43], v[48:49]
	v_lshlrev_b32_e32 v48, 16, v188
	v_and_b32_e32 v49, 0xffff0000, v188
	v_add_f32_e32 v38, 1.0, v38
	v_add_f32_e32 v39, 1.0, v39
	v_mul_f32_e32 v34, 0xbfb8aa3b, v34
	v_mul_f32_e32 v35, 0xbfb8aa3b, v35
	v_pk_mul_f32 v[42:43], v[42:43], v[48:49]
	v_lshlrev_b32_e32 v48, 16, v193
	v_and_b32_e32 v49, 0xffff0000, v193
	v_rcp_f32_e32 v38, v38
	v_rcp_f32_e32 v39, v39
	v_exp_f32_e32 v34, v34
	v_exp_f32_e32 v35, v35
	v_pk_add_f32 v[36:37], v[36:37], v[68:69]
	v_pk_mul_f32 v[44:45], v[44:45], v[48:49]
	v_lshlrev_b32_e32 v48, 16, v189
	v_and_b32_e32 v49, 0xffff0000, v189
	v_add_f32_e32 v40, 1.0, v40
	v_add_f32_e32 v41, 1.0, v41
	v_mul_f32_e32 v36, 0xbfb8aa3b, v36
	v_mul_f32_e32 v37, 0xbfb8aa3b, v37
	v_pk_mul_f32 v[44:45], v[44:45], v[48:49]
	v_rcp_f32_e32 v40, v40
	v_rcp_f32_e32 v41, v41
	v_exp_f32_e32 v36, v36
	v_exp_f32_e32 v37, v37
	v_pk_add_f32 v[30:31], v[30:31], v[78:79]
	v_cvt_pk_bf16_f32 v49, v44, v45
	s_waitcnt vmcnt(15)
	v_lshlrev_b32_e32 v44, 16, v182
	v_and_b32_e32 v45, 0xffff0000, v182
	v_mul_f32_e32 v30, 0xbfb8aa3b, v30
	v_mul_f32_e32 v31, 0xbfb8aa3b, v31
	v_pk_mul_f32 v[38:39], v[38:39], v[44:45]
	v_lshlrev_b32_e32 v44, 16, v178
	v_and_b32_e32 v45, 0xffff0000, v178
	v_add_f32_e32 v34, 1.0, v34
	v_add_f32_e32 v35, 1.0, v35
	v_exp_f32_e32 v30, v30
	v_exp_f32_e32 v31, v31
	v_pk_add_f32 v[32:33], v[32:33], v[80:81]
	v_pk_mul_f32 v[38:39], v[38:39], v[44:45]
	v_lshlrev_b32_e32 v44, 16, v183
	v_and_b32_e32 v45, 0xffff0000, v183
	v_rcp_f32_e32 v34, v34
	v_rcp_f32_e32 v35, v35
	v_mul_f32_e32 v32, 0xbfb8aa3b, v32
	v_mul_f32_e32 v33, 0xbfb8aa3b, v33
	v_pk_mul_f32 v[40:41], v[40:41], v[44:45]
	v_lshlrev_b32_e32 v44, 16, v179
	v_and_b32_e32 v45, 0xffff0000, v179
	v_add_f32_e32 v36, 1.0, v36
	v_add_f32_e32 v37, 1.0, v37
	v_exp_f32_e32 v32, v32
	v_exp_f32_e32 v33, v33
	v_pk_mul_f32 v[40:41], v[40:41], v[44:45]
	v_rcp_f32_e32 v36, v36
	v_rcp_f32_e32 v37, v37
	v_pk_add_f32 v[26:27], v[26:27], v[70:71]
	v_cvt_pk_bf16_f32 v38, v38, v39
	v_cvt_pk_bf16_f32 v39, v40, v41
	v_lshlrev_b32_e32 v40, 16, v184
	v_and_b32_e32 v41, 0xffff0000, v184
	v_add_f32_e32 v30, 1.0, v30
	v_add_f32_e32 v31, 1.0, v31
	v_mul_f32_e32 v26, 0xbfb8aa3b, v26
	v_mul_f32_e32 v27, 0xbfb8aa3b, v27
	v_pk_mul_f32 v[34:35], v[34:35], v[40:41]
	v_lshlrev_b32_e32 v40, 16, v180
	v_and_b32_e32 v41, 0xffff0000, v180
	v_rcp_f32_e32 v30, v30
	v_rcp_f32_e32 v31, v31
	v_exp_f32_e32 v26, v26
	v_exp_f32_e32 v27, v27
	v_pk_add_f32 v[28:29], v[28:29], v[72:73]
	v_pk_mul_f32 v[34:35], v[34:35], v[40:41]
	v_lshlrev_b32_e32 v40, 16, v185
	v_and_b32_e32 v41, 0xffff0000, v185
	v_add_f32_e32 v32, 1.0, v32
	v_add_f32_e32 v33, 1.0, v33
	v_mul_f32_e32 v28, 0xbfb8aa3b, v28
	v_mul_f32_e32 v29, 0xbfb8aa3b, v29
	v_pk_mul_f32 v[36:37], v[36:37], v[40:41]
	v_lshlrev_b32_e32 v40, 16, v181
	v_and_b32_e32 v41, 0xffff0000, v181
	v_rcp_f32_e32 v32, v32
	v_rcp_f32_e32 v33, v33
	v_exp_f32_e32 v28, v28
	v_exp_f32_e32 v29, v29
	v_pk_mul_f32 v[36:37], v[36:37], v[40:41]
	v_cvt_pk_bf16_f32 v40, v34, v35
	s_waitcnt vmcnt(13)
; __device__ __forceinline__ unsigned pk2(float lo, float hi) { const f32x2c_t v = {lo, hi}; return __builtin_bit_cast(unsigned, __builtin_convertvector(v, bf16x2c_t)); }
; __device__ __forceinline__ float bflo(unsigned w) { return __uint_as_float(w << 16); }
; __device__ __forceinline__ float bfhi(unsigned w) { return __uint_as_float(w & 0xffff0000u); }
; __device__ __forceinline__ float sigmoidf_(float v) { return __builtin_amdgcn_rcpf(1.f + __expf(-v)); }
;     __device__ __forceinline__ void operator()(const f32x4 (&acc)[2][2][4][2], const Unit& u, int wr, int wc, int fr, int fq) const {
;     ...
; #pragma unroll
;             for (int m = 0; m < 4; ++m) {
;                 const int row = 256 * u.pm + 128 * ai + 64 * wr + 16 * m + fr;
; #pragma unroll
;                 for (int bj = 0; bj < 2; ++bj) {
;                     const int col = 256 * u.pn + 64 * wc + 32 * bj + 8 * fq;
;                     unsigned w[4];
; #pragma unroll
;                     for (int n = 0; n < 2; ++n) {
;                         const f32x4 a = acc[ai][bj][m][n] + bias[bj][n];
;                         const unsigned ya = y4[m][bj][2 * n], yb = y4[m][bj][2 * n + 1], za = z4[m][bj][2 * n], zb = z4[m][bj][2 * n + 1];
;                         const float o0 = bflo(ya) * sigmoidf_(a[0]) * bflo(za), o1 = bfhi(ya) * sigmoidf_(a[1]) * bfhi(za);
;                         const float o2 = bflo(yb) * sigmoidf_(a[2]) * bflo(zb), o3 = bfhi(yb) * sigmoidf_(a[3]) * bfhi(zb);
;                         w[2 * n] = pk2(o0, o1); w[2 * n + 1] = pk2(o2, o3);
;                     }
;                     *(u32x4*)(MIXED + (size_t)row * 1024 + 512 + col) = (u32x4){w[0], w[1], w[2], w[3]};
;                 }
	v_lshlrev_b32_e32 v34, 16, v174
	v_and_b32_e32 v35, 0xffff0000, v174
	v_pk_add_f32 v[22:23], v[22:23], v[74:75]
	v_pk_mul_f32 v[30:31], v[30:31], v[34:35]
	v_lshlrev_b32_e32 v34, 16, v170
	v_and_b32_e32 v35, 0xffff0000, v170
	v_add_f32_e32 v26, 1.0, v26
	v_add_f32_e32 v27, 1.0, v27
	v_mul_f32_e32 v22, 0xbfb8aa3b, v22
	v_mul_f32_e32 v23, 0xbfb8aa3b, v23
	v_pk_mul_f32 v[30:31], v[30:31], v[34:35]
	v_lshlrev_b32_e32 v34, 16, v175
	v_and_b32_e32 v35, 0xffff0000, v175
	v_rcp_f32_e32 v26, v26
	v_rcp_f32_e32 v27, v27
	v_exp_f32_e32 v22, v22
	v_exp_f32_e32 v23, v23
	v_pk_add_f32 v[24:25], v[24:25], v[76:77]
	v_pk_mul_f32 v[32:33], v[32:33], v[34:35]
	v_lshlrev_b32_e32 v34, 16, v171
	v_and_b32_e32 v35, 0xffff0000, v171
	v_add_f32_e32 v28, 1.0, v28
	v_add_f32_e32 v29, 1.0, v29
	v_mul_f32_e32 v24, 0xbfb8aa3b, v24
	v_mul_f32_e32 v25, 0xbfb8aa3b, v25
	v_pk_mul_f32 v[32:33], v[32:33], v[34:35]
	v_rcp_f32_e32 v28, v28
	v_rcp_f32_e32 v29, v29
	v_exp_f32_e32 v24, v24
	v_exp_f32_e32 v25, v25
	v_cvt_pk_bf16_f32 v30, v30, v31
	v_cvt_pk_bf16_f32 v31, v32, v33
	v_lshlrev_b32_e32 v32, 16, v176
	v_and_b32_e32 v33, 0xffff0000, v176
	v_pk_add_f32 v[18:19], v[18:19], v[66:67]
	v_pk_mul_f32 v[26:27], v[26:27], v[32:33]
	v_lshlrev_b32_e32 v32, 16, v172
	v_and_b32_e32 v33, 0xffff0000, v172
	v_add_f32_e32 v22, 1.0, v22
	v_add_f32_e32 v23, 1.0, v23
	v_mul_f32_e32 v18, 0xbfb8aa3b, v18
	v_mul_f32_e32 v19, 0xbfb8aa3b, v19
	v_pk_mul_f32 v[26:27], v[26:27], v[32:33]
	v_lshlrev_b32_e32 v32, 16, v177
	v_and_b32_e32 v33, 0xffff0000, v177
	v_rcp_f32_e32 v22, v22
	v_rcp_f32_e32 v23, v23
	v_exp_f32_e32 v18, v18
	v_exp_f32_e32 v19, v19
	v_pk_add_f32 v[20:21], v[20:21], v[68:69]
	v_pk_mul_f32 v[28:29], v[28:29], v[32:33]
	v_lshlrev_b32_e32 v32, 16, v173
	v_and_b32_e32 v33, 0xffff0000, v173
	v_add_f32_e32 v24, 1.0, v24
	v_add_f32_e32 v25, 1.0, v25
	v_mul_f32_e32 v20, 0xbfb8aa3b, v20
	v_mul_f32_e32 v21, 0xbfb8aa3b, v21
	v_pk_mul_f32 v[28:29], v[28:29], v[32:33]
	v_rcp_f32_e32 v24, v24
	v_rcp_f32_e32 v25, v25
	v_exp_f32_e32 v20, v20
	v_exp_f32_e32 v21, v21
	v_pk_add_f32 v[14:15], v[14:15], v[78:79]
	v_cvt_pk_bf16_f32 v33, v28, v29
	s_waitcnt vmcnt(11)
	v_lshlrev_b32_e32 v28, 16, v166
	v_and_b32_e32 v29, 0xffff0000, v166
	v_mul_f32_e32 v14, 0xbfb8aa3b, v14
	v_mul_f32_e32 v15, 0xbfb8aa3b, v15
	v_pk_mul_f32 v[22:23], v[22:23], v[28:29]
	v_lshlrev_b32_e32 v28, 16, v162
	v_and_b32_e32 v29, 0xffff0000, v162
	v_add_f32_e32 v18, 1.0, v18
	v_add_f32_e32 v19, 1.0, v19
	v_exp_f32_e32 v14, v14
	v_exp_f32_e32 v15, v15
	v_pk_add_f32 v[16:17], v[16:17], v[80:81]
	v_pk_mul_f32 v[22:23], v[22:23], v[28:29]
	v_lshlrev_b32_e32 v28, 16, v167
	v_and_b32_e32 v29, 0xffff0000, v167
	v_rcp_f32_e32 v18, v18
	v_rcp_f32_e32 v19, v19
	v_mul_f32_e32 v16, 0xbfb8aa3b, v16
	v_mul_f32_e32 v17, 0xbfb8aa3b, v17
	v_pk_mul_f32 v[24:25], v[24:25], v[28:29]
	v_lshlrev_b32_e32 v28, 16, v163
	v_and_b32_e32 v29, 0xffff0000, v163
	v_add_f32_e32 v20, 1.0, v20
	v_add_f32_e32 v21, 1.0, v21
	v_exp_f32_e32 v16, v16
	v_exp_f32_e32 v17, v17
	v_pk_mul_f32 v[24:25], v[24:25], v[28:29]
	v_rcp_f32_e32 v20, v20
	v_rcp_f32_e32 v21, v21
	v_pk_add_f32 v[10:11], v[10:11], v[70:71]
	v_cvt_pk_bf16_f32 v22, v22, v23
	v_cvt_pk_bf16_f32 v23, v24, v25
	v_lshlrev_b32_e32 v24, 16, v168
	v_and_b32_e32 v25, 0xffff0000, v168
	v_add_f32_e32 v14, 1.0, v14
	v_add_f32_e32 v15, 1.0, v15
	v_mul_f32_e32 v10, 0xbfb8aa3b, v10
	v_mul_f32_e32 v11, 0xbfb8aa3b, v11
	v_pk_mul_f32 v[18:19], v[18:19], v[24:25]
	v_lshlrev_b32_e32 v24, 16, v164
	v_and_b32_e32 v25, 0xffff0000, v164
	v_rcp_f32_e32 v14, v14
	v_rcp_f32_e32 v15, v15
	v_exp_f32_e32 v10, v10
	v_exp_f32_e32 v11, v11
	v_pk_add_f32 v[12:13], v[12:13], v[72:73]
	v_pk_mul_f32 v[18:19], v[18:19], v[24:25]
	v_lshlrev_b32_e32 v24, 16, v169
	v_and_b32_e32 v25, 0xffff0000, v169
	v_add_f32_e32 v16, 1.0, v16
	v_add_f32_e32 v17, 1.0, v17
	v_mul_f32_e32 v12, 0xbfb8aa3b, v12
	v_mul_f32_e32 v13, 0xbfb8aa3b, v13
	v_pk_mul_f32 v[20:21], v[20:21], v[24:25]
	v_lshlrev_b32_e32 v24, 16, v165
	v_and_b32_e32 v25, 0xffff0000, v165
	v_rcp_f32_e32 v16, v16
	v_rcp_f32_e32 v17, v17
	v_exp_f32_e32 v12, v12
	v_exp_f32_e32 v13, v13
	v_pk_mul_f32 v[20:21], v[20:21], v[24:25]
	v_cvt_pk_bf16_f32 v24, v18, v19
	s_waitcnt vmcnt(9)
; __device__ __forceinline__ unsigned pk2(float lo, float hi) { const f32x2c_t v = {lo, hi}; return __builtin_bit_cast(unsigned, __builtin_convertvector(v, bf16x2c_t)); }
; __device__ __forceinline__ float bflo(unsigned w) { return __uint_as_float(w << 16); }
; __device__ __forceinline__ float bfhi(unsigned w) { return __uint_as_float(w & 0xffff0000u); }
; __device__ __forceinline__ float sigmoidf_(float v) { return __builtin_amdgcn_rcpf(1.f + __expf(-v)); }
; #define PG8_WAIT_V(n) asm volatile("s_waitcnt vmcnt(" #n ")" ::: "memory")
; #define PG8_BAR __builtin_amdgcn_s_barrier()
; template <int LDA, int LDB, int KK, bool AFTER = false, bool ALIGN_EPI = true, bool SP2 = true, class Epi, class Sched>
; __device__ __forceinline__ void gemm_phase(LAS unsigned char* lds, const Gemm g, const Sched& S, const Epi& E) {
;     ...
;     PG8_WAIT_V(0);
;     if constexpr (!ALIGN_EPI) { if (wr == 0) PG8_BAR; }
;     PG8_BAR;
;     __device__ __forceinline__ void operator()(const f32x4 (&acc)[2][2][4][2], const Unit& u, int wr, int wc, int fr, int fq) const {
;     ...
; #pragma unroll
;             for (int m = 0; m < 4; ++m) {
;                 const int row = 256 * u.pm + 128 * ai + 64 * wr + 16 * m + fr;
; #pragma unroll
;                 for (int bj = 0; bj < 2; ++bj) {
;                     const int col = 256 * u.pn + 64 * wc + 32 * bj + 8 * fq;
;                     unsigned w[4];
; #pragma unroll
;                     for (int n = 0; n < 2; ++n) {
;                         const f32x4 a = acc[ai][bj][m][n] + bias[bj][n];
;                         const unsigned ya = y4[m][bj][2 * n], yb = y4[m][bj][2 * n + 1], za = z4[m][bj][2 * n], zb = z4[m][bj][2 * n + 1];
;                         const float o0 = bflo(ya) * sigmoidf_(a[0]) * bflo(za), o1 = bfhi(ya) * sigmoidf_(a[1]) * bfhi(za);
;                         const float o2 = bflo(yb) * sigmoidf_(a[2]) * bflo(zb), o3 = bfhi(yb) * sigmoidf_(a[3]) * bfhi(zb);
;                         w[2 * n] = pk2(o0, o1); w[2 * n + 1] = pk2(o2, o3);
;                     }
;                     *(u32x4*)(MIXED + (size_t)row * 1024 + 512 + col) = (u32x4){w[0], w[1], w[2], w[3]};
;                 }
	v_lshlrev_b32_e32 v18, 16, v158
	v_and_b32_e32 v19, 0xffff0000, v158
	v_pk_add_f32 v[6:7], v[6:7], v[74:75]
	v_pk_mul_f32 v[14:15], v[14:15], v[18:19]
	v_lshlrev_b32_e32 v18, 16, v154
	v_and_b32_e32 v19, 0xffff0000, v154
	v_add_f32_e32 v10, 1.0, v10
	v_add_f32_e32 v11, 1.0, v11
	v_mul_f32_e32 v6, 0xbfb8aa3b, v6
	v_mul_f32_e32 v7, 0xbfb8aa3b, v7
	v_pk_mul_f32 v[14:15], v[14:15], v[18:19]
	v_lshlrev_b32_e32 v18, 16, v159
	v_and_b32_e32 v19, 0xffff0000, v159
	v_rcp_f32_e32 v10, v10
	v_rcp_f32_e32 v11, v11
	v_exp_f32_e32 v6, v6
	v_exp_f32_e32 v7, v7
	v_pk_add_f32 v[8:9], v[8:9], v[76:77]
	v_pk_mul_f32 v[16:17], v[16:17], v[18:19]
	v_lshlrev_b32_e32 v18, 16, v155
	v_and_b32_e32 v19, 0xffff0000, v155
	v_add_f32_e32 v12, 1.0, v12
	v_add_f32_e32 v13, 1.0, v13
	v_mul_f32_e32 v8, 0xbfb8aa3b, v8
	v_mul_f32_e32 v9, 0xbfb8aa3b, v9
	v_pk_mul_f32 v[16:17], v[16:17], v[18:19]
	v_rcp_f32_e32 v12, v12
	v_rcp_f32_e32 v13, v13
	v_exp_f32_e32 v8, v8
	v_exp_f32_e32 v9, v9
	v_cvt_pk_bf16_f32 v14, v14, v15
	v_cvt_pk_bf16_f32 v15, v16, v17
	v_lshlrev_b32_e32 v16, 16, v160
	v_and_b32_e32 v17, 0xffff0000, v160
	v_pk_add_f32 v[2:3], v[2:3], v[66:67]
	v_pk_mul_f32 v[10:11], v[10:11], v[16:17]
	v_lshlrev_b32_e32 v16, 16, v156
	v_and_b32_e32 v17, 0xffff0000, v156
	v_add_f32_e32 v6, 1.0, v6
	v_add_f32_e32 v7, 1.0, v7
	v_mul_f32_e32 v2, 0xbfb8aa3b, v2
	v_mul_f32_e32 v3, 0xbfb8aa3b, v3
	v_pk_mul_f32 v[10:11], v[10:11], v[16:17]
	v_lshlrev_b32_e32 v16, 16, v161
	v_and_b32_e32 v17, 0xffff0000, v161
	v_rcp_f32_e32 v6, v6
	v_rcp_f32_e32 v7, v7
	v_exp_f32_e32 v2, v2
	v_exp_f32_e32 v3, v3
	v_pk_add_f32 v[4:5], v[4:5], v[68:69]
	v_pk_mul_f32 v[12:13], v[12:13], v[16:17]
	v_lshlrev_b32_e32 v16, 16, v157
	v_and_b32_e32 v17, 0xffff0000, v157
	v_add_f32_e32 v8, 1.0, v8
	v_add_f32_e32 v9, 1.0, v9
	v_mul_f32_e32 v4, 0xbfb8aa3b, v4
	v_mul_f32_e32 v5, 0xbfb8aa3b, v5
	v_pk_mul_f32 v[12:13], v[12:13], v[16:17]
	v_rcp_f32_e32 v8, v8
	v_rcp_f32_e32 v9, v9
	v_exp_f32_e32 v4, v4
	v_exp_f32_e32 v5, v5
	v_cvt_pk_bf16_f32 v17, v12, v13
	s_waitcnt vmcnt(7)
	v_lshlrev_b32_e32 v12, 16, v142
	v_and_b32_e32 v13, 0xffff0000, v142
	v_pk_mul_f32 v[6:7], v[6:7], v[12:13]
	v_lshlrev_b32_e32 v12, 16, v138
	v_and_b32_e32 v13, 0xffff0000, v138
	v_add_f32_e32 v2, 1.0, v2
	v_add_f32_e32 v3, 1.0, v3
	v_pk_mul_f32 v[6:7], v[6:7], v[12:13]
	v_lshlrev_b32_e32 v12, 16, v143
	v_and_b32_e32 v13, 0xffff0000, v143
	v_rcp_f32_e32 v2, v2
	v_rcp_f32_e32 v3, v3
	v_pk_mul_f32 v[8:9], v[8:9], v[12:13]
	v_lshlrev_b32_e32 v12, 16, v139
	v_and_b32_e32 v13, 0xffff0000, v139
	v_add_f32_e32 v4, 1.0, v4
	v_add_f32_e32 v5, 1.0, v5
	v_pk_mul_f32 v[8:9], v[8:9], v[12:13]
	v_rcp_f32_e32 v4, v4
	v_rcp_f32_e32 v5, v5
	v_cvt_pk_bf16_f32 v6, v6, v7
	v_cvt_pk_bf16_f32 v7, v8, v9
	v_lshlrev_b32_e32 v8, 16, v144
	v_and_b32_e32 v9, 0xffff0000, v144
	v_pk_mul_f32 v[2:3], v[2:3], v[8:9]
	v_lshlrev_b32_e32 v8, 16, v140
	v_and_b32_e32 v9, 0xffff0000, v140
	v_cvt_pk_bf16_f32 v64, v58, v59
	v_lshl_add_u64 v[58:59], v[146:147], 0, s[0:1]
	s_mov_b64 s[0:1], 0x48000
	v_pk_mul_f32 v[2:3], v[2:3], v[8:9]
	v_lshlrev_b32_e32 v8, 16, v145
	v_and_b32_e32 v9, 0xffff0000, v145
	v_cvt_pk_bf16_f32 v48, v42, v43
	v_lshl_add_u64 v[42:43], v[146:147], 0, s[0:1]
	s_mov_b64 s[0:1], 0x50000
	v_pk_mul_f32 v[4:5], v[4:5], v[8:9]
	v_lshlrev_b32_e32 v8, 16, v141
	v_and_b32_e32 v9, 0xffff0000, v141
	v_cvt_pk_bf16_f32 v32, v26, v27
	v_lshl_add_u64 v[26:27], v[146:147], 0, s[0:1]
	s_mov_b64 s[0:1], 0x58000
	v_pk_mul_f32 v[4:5], v[4:5], v[8:9]
	v_cvt_pk_bf16_f32 v57, v52, v53
	v_cvt_pk_bf16_f32 v41, v36, v37
	v_cvt_pk_bf16_f32 v25, v20, v21
	v_cvt_pk_bf16_f32 v16, v10, v11
	v_lshl_add_u64 v[10:11], v[146:147], 0, s[0:1]
	v_cvt_pk_bf16_f32 v8, v2, v3
	v_cvt_pk_bf16_f32 v9, v4, v5
	global_store_dwordx4 v[58:59], v[62:65], off offset:1024
	global_store_dwordx4 v[58:59], v[54:57], off offset:1088
	global_store_dwordx4 v[42:43], v[46:49], off offset:1024
	global_store_dwordx4 v[42:43], v[38:41], off offset:1088
	global_store_dwordx4 v[26:27], v[30:33], off offset:1024
	global_store_dwordx4 v[26:27], v[22:25], off offset:1088
	global_store_dwordx4 v[10:11], v[14:17], off offset:1024
	global_store_dwordx4 v[10:11], v[6:9], off offset:1088
	v_mov_b32_e32 v2, v234
	s_barrier
